# FoX loop: packed v_pk_add_f32 row-sum chain split into scalar v_add pairs (doc 7.5)
# baseline (speedup 1.0000x reference)
; template <int DV, int NMAP>
; __device__ __forceinline__ void attn_unit(LAS unsigned char* lds, const bf16_t* U, bf16_t* MIX, const float* logf, int b, int h, int qb, float lam, float slope2, const float* gn, float outscale, const int tid) {
;     ...
;             s16x4 lo[2][4], hh[2][4];
; #pragma unroll
;             for (int e = 0; e < 2; ++e)
; #pragma unroll
;                 for (int s = 0; s < 4; ++s) { lo[e][s] = vtr(Vb + e * 4096 + s * 1024); hh[e][s] = vtr(Vb + e * 4096 + s * 1024 + 512); }
;             __builtin_amdgcn_sched_barrier(0);
;             {
;                 float s0 = 0.f, s1 = 0.f, s2 = 0.f, s3 = 0.f;
; #pragma unroll
;                 for (int r = 0; r < 16; r += 2) { p0[r] = __builtin_amdgcn_exp2f(p0[r] - m_run); p0[r + 1] = __builtin_amdgcn_exp2f(p0[r + 1] - m_run); p1[r] = __builtin_amdgcn_exp2f(p1[r] - m_run); p1[r + 1] = __builtin_amdgcn_exp2f(p1[r + 1] - m_run);
;                     s0 += p0[r]; s1 += p0[r + 1]; s2 += p1[r]; s3 += p1[r + 1]; }
;                 l_run += (s0 + s1) + (s2 + s3);
;             }
;             bf16x8 pk[4];
;             {
;                 u32x4 w;
;                 w.x = pk_bf16(p0[0], p0[1]); w.y = pk_bf16(p0[2], p0[3]); w.z = pk_bf16(p0[4], p0[5]); w.w = pk_bf16(p0[6], p0[7]); pk[0] = __builtin_bit_cast(bf16x8, w);
;                 w.x = pk_bf16(p0[8], p0[9]); w.y = pk_bf16(p0[10], p0[11]); w.z = pk_bf16(p0[12], p0[13]); w.w = pk_bf16(p0[14], p0[15]); pk[1] = __builtin_bit_cast(bf16x8, w);
;                 w.x = pk_bf16(p1[0], p1[1]); w.y = pk_bf16(p1[2], p1[3]); w.z = pk_bf16(p1[4], p1[5]); w.w = pk_bf16(p1[6], p1[7]); pk[2] = __builtin_bit_cast(bf16x8, w);
;                 w.x = pk_bf16(p1[8], p1[9]); w.y = pk_bf16(p1[10], p1[11]); w.z = pk_bf16(p1[12], p1[13]); w.w = pk_bf16(p1[14], p1[15]); pk[3] = __builtin_bit_cast(bf16x8, w);
;             }
;             __builtin_amdgcn_sched_barrier(0);
;             if (NDB == 4) {
;                 s16x4 lo2[2][4], hh2[2][4];
; #pragma unroll
;                 for (int e = 0; e < 2; ++e)
; #pragma unroll
;                     for (int s = 0; s < 4; ++s) { lo2[e][s] = vtr(Vb + (2 + e) * 4096 + s * 1024); hh2[e][s] = vtr(Vb + (2 + e) * 4096 + s * 1024 + 512); }
;                 __builtin_amdgcn_sched_barrier(0);
; #pragma unroll
;                 for (int s = 0; s < 4; ++s)
; #pragma unroll
;                     for (int e = 0; e < 2; ++e) {
.LBB0_202:
	v_lshl_add_u32 v84, s62, 13, v141
	ds_read_b64_tr_b16 v[108:109], v84 offset:33792
	ds_read_b64_tr_b16 v[110:111], v84 offset:34304
	ds_read_b64_tr_b16 v[112:113], v84 offset:34816
	ds_read_b64_tr_b16 v[114:115], v84 offset:35328
	ds_read_b64_tr_b16 v[90:91], v84 offset:35840
	ds_read_b64_tr_b16 v[92:93], v84 offset:36352
	ds_read_b64_tr_b16 v[86:87], v84 offset:36864
	ds_read_b64_tr_b16 v[88:89], v84 offset:37376
	ds_read_b64_tr_b16 v[116:117], v84 offset:37888
	ds_read_b64_tr_b16 v[118:119], v84 offset:38400
	ds_read_b64_tr_b16 v[136:137], v84 offset:38912
	ds_read_b64_tr_b16 v[138:139], v84 offset:39424
	ds_read_b64_tr_b16 v[94:95], v84 offset:39936
	ds_read_b64_tr_b16 v[96:97], v84 offset:40448
	ds_read_b64_tr_b16 v[82:83], v84 offset:40960
	ds_read_b64_tr_b16 v[84:85], v84 offset:41472
	v_sub_f32_e32 v51, v51, v104
	v_sub_f32_e32 v34, v34, v104
	v_exp_f32_e32 v120, v51
	v_exp_f32_e32 v51, v34
	v_sub_f32_e32 v34, v35, v104
	v_exp_f32_e32 v121, v34
	v_sub_f32_e32 v34, v52, v104
	v_exp_f32_e32 v52, v34
	v_sub_f32_e32 v34, v53, v104
	v_exp_f32_e32 v148, v34
	v_sub_f32_e32 v34, v36, v104
	v_exp_f32_e32 v53, v34
	v_sub_f32_e32 v34, v37, v104
	v_exp_f32_e32 v149, v34
	v_sub_f32_e32 v34, v54, v104
	v_exp_f32_e32 v54, v34
	v_sub_f32_e32 v34, v55, v104
	v_exp_f32_e32 v150, v34
	v_sub_f32_e32 v34, v38, v104
	v_exp_f32_e32 v55, v34
	v_sub_f32_e32 v34, v39, v104
	v_exp_f32_e32 v151, v34
	v_sub_f32_e32 v34, v56, v104
	v_exp_f32_e32 v56, v34
	v_sub_f32_e32 v34, v57, v104
	v_exp_f32_e32 v152, v34
	v_sub_f32_e32 v34, v40, v104
	v_exp_f32_e32 v57, v34
	v_sub_f32_e32 v34, v41, v104
	v_exp_f32_e32 v153, v34
	v_sub_f32_e32 v34, v58, v104
	v_exp_f32_e32 v58, v34
	v_sub_f32_e32 v34, v59, v104
	v_exp_f32_e32 v154, v34
	v_sub_f32_e32 v34, v42, v104
	v_exp_f32_e32 v59, v34
	v_sub_f32_e32 v34, v43, v104
	v_exp_f32_e32 v155, v34
	v_sub_f32_e32 v34, v60, v104
	v_exp_f32_e32 v60, v34
	v_sub_f32_e32 v34, v61, v104
	v_exp_f32_e32 v156, v34
	v_sub_f32_e32 v34, v44, v104
	v_exp_f32_e32 v61, v34
	v_sub_f32_e32 v34, v45, v104
	v_exp_f32_e32 v157, v34
	v_sub_f32_e32 v34, v62, v104
	v_exp_f32_e32 v62, v34
	v_sub_f32_e32 v34, v63, v104
	v_exp_f32_e32 v158, v34
	v_sub_f32_e32 v34, v46, v104
	v_sub_f32_e32 v50, v50, v104
	v_exp_f32_e32 v63, v34
	v_sub_f32_e32 v34, v47, v104
	v_exp_f32_e32 v50, v50
	v_exp_f32_e32 v159, v34
	v_sub_f32_e32 v34, v64, v104
	v_exp_f32_e32 v64, v34
	v_sub_f32_e32 v34, v65, v104
	v_exp_f32_e32 v160, v34
	v_sub_f32_e32 v34, v48, v104
	v_exp_f32_e32 v65, v34
	v_sub_f32_e32 v34, v49, v104
	v_exp_f32_e32 v161, v34
	v_add_f32_e32 v34, 0, v50
	v_add_f32_e32 v35, 0, v51
	v_add_f32_e32 v36, 0, v120
	v_add_f32_e32 v37, 0, v121
	v_add_f32_e32 v34, v52, v34
	v_add_f32_e32 v35, v53, v35
	v_add_f32_e32 v36, v148, v36
	v_add_f32_e32 v37, v149, v37
	v_add_f32_e32 v34, v54, v34
	v_add_f32_e32 v35, v55, v35
	v_add_f32_e32 v36, v150, v36
	v_add_f32_e32 v37, v151, v37
	v_add_f32_e32 v34, v56, v34
	v_add_f32_e32 v35, v57, v35
	v_add_f32_e32 v36, v152, v36
	v_add_f32_e32 v37, v153, v37
	v_add_f32_e32 v34, v58, v34
	v_add_f32_e32 v35, v59, v35
	v_add_f32_e32 v36, v154, v36
	v_add_f32_e32 v37, v155, v37
	v_add_f32_e32 v34, v60, v34
	v_add_f32_e32 v35, v61, v35
	v_add_f32_e32 v36, v156, v36
	v_add_f32_e32 v37, v157, v37
	v_add_f32_e32 v34, v62, v34
	v_add_f32_e32 v35, v63, v35
	v_add_f32_e32 v36, v158, v36
	v_add_f32_e32 v37, v159, v37
	v_add_f32_e32 v34, v64, v34
	v_add_f32_e32 v35, v65, v35
	v_add_f32_e32 v36, v160, v36
	v_add_f32_e32 v37, v161, v37
	s_nop 0
	v_add_f32_e32 v34, v34, v36
	v_add_f32_e32 v35, v35, v37
	s_nop 0
	v_add_f32_e32 v107, v34, v35
	v_cvt_pk_bf16_f32 v34, v50, v120
	v_cvt_pk_bf16_f32 v35, v52, v148
	v_cvt_pk_bf16_f32 v36, v54, v150
	v_cvt_pk_bf16_f32 v37, v56, v152
	v_cvt_pk_bf16_f32 v38, v58, v154
	v_cvt_pk_bf16_f32 v39, v60, v156
	v_cvt_pk_bf16_f32 v40, v62, v158
	v_cvt_pk_bf16_f32 v41, v64, v160
	v_cvt_pk_bf16_f32 v42, v51, v121
	v_cvt_pk_bf16_f32 v43, v53, v149
	v_cvt_pk_bf16_f32 v44, v55, v151
	v_cvt_pk_bf16_f32 v45, v57, v153
	v_cvt_pk_bf16_f32 v46, v59, v155
	v_cvt_pk_bf16_f32 v47, v61, v157
	v_cvt_pk_bf16_f32 v48, v63, v159
	v_cvt_pk_bf16_f32 v49, v65, v161
	s_waitcnt lgkmcnt(14)
	v_mfma_f32_32x32x16_bf16 v[2:17], v[108:111], v[34:37], v[2:17]
	v_add_f32_e32 v105, v105, v107
	s_waitcnt lgkmcnt(6)
	v_mfma_f32_32x32x16_bf16 v[18:33], v[116:119], v[34:37], v[18:33]
	v_mfma_f32_32x32x16_bf16 v[2:17], v[112:115], v[38:41], v[2:17]
	s_waitcnt lgkmcnt(4)
	v_mfma_f32_32x32x16_bf16 v[18:33], v[136:139], v[38:41], v[18:33]
	v_mfma_f32_32x32x16_bf16 v[2:17], v[90:93], v[42:45], v[2:17]
	s_waitcnt lgkmcnt(2)
	v_mfma_f32_32x32x16_bf16 v[18:33], v[94:97], v[42:45], v[18:33]
	v_mfma_f32_32x32x16_bf16 v[2:17], v[86:89], v[46:49], v[2:17]
	s_waitcnt lgkmcnt(0)
	v_mfma_f32_32x32x16_bf16 v[18:33], v[82:85], v[46:49], v[18:33]
